# GEMM main loop: loop-exit compare and counter copy moved from after the last barrier into load segment 4 after its last DMA
# speedup vs baseline: 1.0033x; 1.0022x over previous
; #define PG8_STAGE(bufoff, gbase, voff) do { _Pragma("unroll") for (int _i = 0; _i < 2; ++_i) \
;         __builtin_amdgcn_global_load_lds((const unsigned*)((const char*)(gbase) + (voff)[_i]), (LAS unsigned*)(lds + (bufoff) + ldsw + _i * 8192), 16, 0, 0); } while (0)
; #define PG8_LDA(dst, b, h) do { _Pragma("unroll") for (int m = 0; m < 4; ++m) _Pragma("unroll") for (int k = 0; k < 2; ++k) dst[m][k] = *(const LAS bf16x8*)(lds + PG8_SA(b, h) + aoff + m * 2048 + k * 1024); } while (0)
; #define PG8_LDB(dst, b, h) do { _Pragma("unroll") for (int n = 0; n < 2; ++n) _Pragma("unroll") for (int k = 0; k < 2; ++k) dst[n][k] = *(const LAS bf16x8*)(lds + PG8_SB(b, h) + boff + n * 2048 + k * 1024); } while (0)
; #define PG8_MMA(ai, bj, At, Bt) do { __builtin_amdgcn_s_setprio(1); _Pragma("unroll") for (int m = 0; m < 4; ++m) _Pragma("unroll") for (int n = 0; n < 2; ++n) _Pragma("unroll") for (int k = 0; k < 2; ++k) \
;         acc[ai][bj][m][n] = __builtin_amdgcn_mfma_f32_16x16x32_bf16(Bt[n][k], At[m][k], acc[ai][bj][m][n], 0, 0, 0); __builtin_amdgcn_s_setprio(0); } while (0)
; #define PG8_WAIT_V(n) asm volatile("s_waitcnt vmcnt(" #n ")" ::: "memory")
; #define PG8_WAIT_L(n) asm volatile("s_waitcnt lgkmcnt(" #n ")" ::: "memory")
; #define PG8_BAR __builtin_amdgcn_s_barrier()
; #define PG8_SCHED __builtin_amdgcn_sched_barrier(0)
; __device__ __forceinline__ void gemm_phase(LAS unsigned char* lds, const GemmD g, const Sched& S, const Epi& E) {
;     ...
;         for (int t = 0; t < nt; t += 2) {
;             const bool last = (t == nt - 2);
;             const char* a1 = cA + (size_t)(t + 1) * kstep;
;             const char* a2 = last ? nA : cA + (size_t)(t + 2) * kstep; const char* b2 = last ? nB : cB + (size_t)(t + 2) * kstep;
;             const char* a3 = a2 + kstep; const char* b3 = b2 + kstep;
;             PG8_LDB(B0, 0, 0); PG8_LDB(B1, 0, 1); PG8_SCHED; PG8_LDA(At, 0, 0); PG8_STAGE(PG8_SA(1, 1), a1 + hstepA, voffA);
;             PG8_WAIT_V(8); PG8_WAIT_L(0); PG8_BAR; PG8_MMA(0, 0, At, B0); PG8_MMA(0, 1, At, B1); PG8_BAR; PG8_SCHED;
;             PG8_LDA(At, 0, 1); PG8_STAGE(PG8_SB(0, 0), b2, voffB); PG8_STAGE(PG8_SB(0, 1), b2 + hstepB, voffB); PG8_STAGE(PG8_SA(0, 0), a2, voffA);
;             PG8_WAIT_V(8); PG8_WAIT_L(0); PG8_BAR; PG8_MMA(1, 0, At, B0); PG8_MMA(1, 1, At, B1); PG8_BAR; PG8_SCHED;
.Lprio_done:
	v_add_u32_e32 v240, 0x10000, v160
	v_add_u32_e32 v241, 0x14000, v160
	v_add_u32_e32 v242, 0x18000, v160
	v_add_u32_e32 v243, 0x1c000, v160
	ds_read_b128 v[130:133], v240
	ds_read_b128 v[146:149], v240 offset:1024
	ds_read_b128 v[150:153], v240 offset:2048
	ds_read_b128 v[154:157], v240 offset:3072
	ds_read_b128 v[162:165], v241
	ds_read_b128 v[166:169], v241 offset:1024
	ds_read_b128 v[170:173], v241 offset:2048
	ds_read_b128 v[174:177], v241 offset:3072
	s_add_i32 m0, s31, 0xc000
	ds_read_b128 v[182:185], v161
	ds_read_b128 v[186:189], v161 offset:1024
	ds_read_b128 v[190:193], v161 offset:2048
	ds_read_b128 v[216:219], v161 offset:3072
	ds_read_b128 v[220:223], v161 offset:4096
	ds_read_b128 v[224:227], v161 offset:5120
	ds_read_b128 v[228:231], v161 offset:6144
	ds_read_b128 v[236:239], v161 offset:7168
	global_load_lds_dwordx4 v142, s[8:9]
	s_add_i32 m0, s31, 0xe000
	s_nop 0
	global_load_lds_dwordx4 v144, s[8:9]
	s_add_i32 s92, s26, 2
	s_add_u32 s93, s8, 0x80
	s_addc_u32 s27, s9, 0
	s_add_i32 s22, 0, 0x10000
	s_cmp_eq_u32 s11, s26
	s_cselect_b32 s27, s1, s27
	s_cselect_b32 s26, s0, s93
	s_cselect_b32 vcc_hi, s17, s35
	s_cselect_b32 vcc_lo, s16, s34
	s_add_i32 s23, 0, 0x14000
	s_waitcnt vmcnt(8)
	s_waitcnt lgkmcnt(0)
	s_barrier
	s_waitcnt lgkmcnt(0)
	v_mfma_f32_16x16x32_bf16 v[126:129], v[130:133], v[182:185], 0
	v_mfma_f32_16x16x32_bf16 v[122:125], v[150:153], v[182:185], 0
	v_mfma_f32_16x16x32_bf16 v[110:113], v[130:133], v[190:193], 0
	v_mfma_f32_16x16x32_bf16 v[106:109], v[150:153], v[190:193], 0
	v_mfma_f32_16x16x32_bf16 v[94:97], v[130:133], v[220:223], 0
	v_mfma_f32_16x16x32_bf16 v[90:93], v[150:153], v[220:223], 0
	v_mfma_f32_16x16x32_bf16 v[78:81], v[130:133], v[228:231], 0
	v_mfma_f32_16x16x32_bf16 v[74:77], v[150:153], v[228:231], 0
	v_mfma_f32_16x16x32_bf16 v[126:129], v[146:149], v[186:189], v[126:129]
	v_mfma_f32_16x16x32_bf16 v[122:125], v[154:157], v[186:189], v[122:125]
	v_mfma_f32_16x16x32_bf16 v[110:113], v[146:149], v[216:219], v[110:113]
	v_mfma_f32_16x16x32_bf16 v[106:109], v[154:157], v[216:219], v[106:109]
	v_mfma_f32_16x16x32_bf16 v[94:97], v[146:149], v[224:227], v[94:97]
	v_mfma_f32_16x16x32_bf16 v[90:93], v[154:157], v[224:227], v[90:93]
	v_mfma_f32_16x16x32_bf16 v[78:81], v[146:149], v[236:239], v[78:81]
	v_mfma_f32_16x16x32_bf16 v[74:77], v[154:157], v[236:239], v[74:77]
	v_mfma_f32_16x16x32_bf16 v[118:121], v[162:165], v[182:185], 0
	v_mfma_f32_16x16x32_bf16 v[114:117], v[170:173], v[182:185], 0
	v_mfma_f32_16x16x32_bf16 v[102:105], v[162:165], v[190:193], 0
	v_mfma_f32_16x16x32_bf16 v[98:101], v[170:173], v[190:193], 0
	v_mfma_f32_16x16x32_bf16 v[86:89], v[162:165], v[220:223], 0
	v_mfma_f32_16x16x32_bf16 v[82:85], v[170:173], v[220:223], 0
	v_mfma_f32_16x16x32_bf16 v[70:73], v[162:165], v[228:231], 0
	v_mfma_f32_16x16x32_bf16 v[66:69], v[170:173], v[228:231], 0
	v_mfma_f32_16x16x32_bf16 v[118:121], v[166:169], v[186:189], v[118:121]
	v_mfma_f32_16x16x32_bf16 v[114:117], v[174:177], v[186:189], v[114:117]
	v_mfma_f32_16x16x32_bf16 v[102:105], v[166:169], v[216:219], v[102:105]
	v_mfma_f32_16x16x32_bf16 v[98:101], v[174:177], v[216:219], v[98:101]
	v_mfma_f32_16x16x32_bf16 v[86:89], v[166:169], v[224:227], v[86:89]
	v_mfma_f32_16x16x32_bf16 v[82:85], v[174:177], v[224:227], v[82:85]
	v_mfma_f32_16x16x32_bf16 v[70:73], v[166:169], v[236:239], v[70:73]
	v_mfma_f32_16x16x32_bf16 v[66:69], v[174:177], v[236:239], v[66:69]
	s_barrier
	s_add_i32 s22, s22, s30
	s_mov_b32 m0, s22
	ds_read_b128 v[182:185], v161 offset:16384
	ds_read_b128 v[186:189], v161 offset:17408
	ds_read_b128 v[190:193], v161 offset:18432
	ds_read_b128 v[216:219], v161 offset:19456
	ds_read_b128 v[220:223], v161 offset:20480
	ds_read_b128 v[224:227], v161 offset:21504
	ds_read_b128 v[228:231], v161 offset:22528
	ds_read_b128 v[236:239], v161 offset:23552
	global_load_lds_dwordx4 v136, vcc
	s_add_i32 m0, s22, 0x2000
	s_add_i32 s22, s23, s30
	global_load_lds_dwordx4 v140, vcc
	s_mov_b32 m0, s22
	s_nop 0
	global_load_lds_dwordx4 v253, vcc
	s_add_i32 m0, s22, 0x2000
	s_nop 0
	global_load_lds_dwordx4 v254, vcc
	s_mov_b32 m0, s31
	s_add_u32 s34, s34, 0x100
	global_load_lds_dwordx4 v134, s[26:27]
	s_mov_b32 m0, s14
	s_addc_u32 s35, s35, 0
	global_load_lds_dwordx4 v138, s[26:27]
	s_waitcnt vmcnt(8)
	s_waitcnt lgkmcnt(0)
	s_barrier
	s_waitcnt lgkmcnt(0)
	v_mfma_f32_16x16x32_bf16 v[62:65], v[130:133], v[182:185], 0
	v_mfma_f32_16x16x32_bf16 v[58:61], v[150:153], v[182:185], 0
	v_mfma_f32_16x16x32_bf16 v[46:49], v[130:133], v[190:193], 0
	v_mfma_f32_16x16x32_bf16 v[42:45], v[150:153], v[190:193], 0
	v_mfma_f32_16x16x32_bf16 v[30:33], v[130:133], v[220:223], 0
	v_mfma_f32_16x16x32_bf16 v[26:29], v[150:153], v[220:223], 0
	v_mfma_f32_16x16x32_bf16 v[14:17], v[130:133], v[228:231], 0
	v_mfma_f32_16x16x32_bf16 v[10:13], v[150:153], v[228:231], 0
	v_mfma_f32_16x16x32_bf16 v[62:65], v[146:149], v[186:189], v[62:65]
	v_mfma_f32_16x16x32_bf16 v[58:61], v[154:157], v[186:189], v[58:61]
	v_mfma_f32_16x16x32_bf16 v[46:49], v[146:149], v[216:219], v[46:49]
	v_mfma_f32_16x16x32_bf16 v[42:45], v[154:157], v[216:219], v[42:45]
	v_mfma_f32_16x16x32_bf16 v[30:33], v[146:149], v[224:227], v[30:33]
	v_mfma_f32_16x16x32_bf16 v[26:29], v[154:157], v[224:227], v[26:29]
	v_mfma_f32_16x16x32_bf16 v[14:17], v[146:149], v[236:239], v[14:17]
	v_mfma_f32_16x16x32_bf16 v[10:13], v[154:157], v[236:239], v[10:13]
	v_mfma_f32_16x16x32_bf16 v[54:57], v[162:165], v[182:185], 0
	v_mfma_f32_16x16x32_bf16 v[50:53], v[170:173], v[182:185], 0
	v_mfma_f32_16x16x32_bf16 v[38:41], v[162:165], v[190:193], 0
	v_mfma_f32_16x16x32_bf16 v[34:37], v[170:173], v[190:193], 0
	v_mfma_f32_16x16x32_bf16 v[22:25], v[162:165], v[220:223], 0
	v_mfma_f32_16x16x32_bf16 v[18:21], v[170:173], v[220:223], 0
	v_mfma_f32_16x16x32_bf16 v[6:9], v[162:165], v[228:231], 0
	v_mfma_f32_16x16x32_bf16 v[2:5], v[170:173], v[228:231], 0
	v_mfma_f32_16x16x32_bf16 v[54:57], v[166:169], v[186:189], v[54:57]
	v_mfma_f32_16x16x32_bf16 v[50:53], v[174:177], v[186:189], v[50:53]
	v_mfma_f32_16x16x32_bf16 v[38:41], v[166:169], v[216:219], v[38:41]
	v_mfma_f32_16x16x32_bf16 v[34:37], v[174:177], v[216:219], v[34:37]
	v_mfma_f32_16x16x32_bf16 v[22:25], v[166:169], v[224:227], v[22:25]
	v_mfma_f32_16x16x32_bf16 v[18:21], v[174:177], v[224:227], v[18:21]
	v_mfma_f32_16x16x32_bf16 v[6:9], v[166:169], v[236:239], v[6:9]
	v_mfma_f32_16x16x32_bf16 v[2:5], v[174:177], v[236:239], v[2:5]
	s_barrier
; #define PG8_STAGE(bufoff, gbase, voff) do { _Pragma("unroll") for (int _i = 0; _i < 2; ++_i) \
;         __builtin_amdgcn_global_load_lds((const unsigned*)((const char*)(gbase) + (voff)[_i]), (LAS unsigned*)(lds + (bufoff) + ldsw + _i * 8192), 16, 0, 0); } while (0)
; #define PG8_LDA(dst, b, h) do { _Pragma("unroll") for (int m = 0; m < 4; ++m) _Pragma("unroll") for (int k = 0; k < 2; ++k) dst[m][k] = *(const LAS bf16x8*)(lds + PG8_SA(b, h) + aoff + m * 2048 + k * 1024); } while (0)
; #define PG8_LDB(dst, b, h) do { _Pragma("unroll") for (int n = 0; n < 2; ++n) _Pragma("unroll") for (int k = 0; k < 2; ++k) dst[n][k] = *(const LAS bf16x8*)(lds + PG8_SB(b, h) + boff + n * 2048 + k * 1024); } while (0)
; #define PG8_MMA(ai, bj, At, Bt) do { __builtin_amdgcn_s_setprio(1); _Pragma("unroll") for (int m = 0; m < 4; ++m) _Pragma("unroll") for (int n = 0; n < 2; ++n) _Pragma("unroll") for (int k = 0; k < 2; ++k) \
;         acc[ai][bj][m][n] = __builtin_amdgcn_mfma_f32_16x16x32_bf16(Bt[n][k], At[m][k], acc[ai][bj][m][n], 0, 0, 0); __builtin_amdgcn_s_setprio(0); } while (0)
; #define PG8_WAIT_V(n) asm volatile("s_waitcnt vmcnt(" #n ")" ::: "memory")
; #define PG8_WAIT_L(n) asm volatile("s_waitcnt lgkmcnt(" #n ")" ::: "memory")
; #define PG8_BAR __builtin_amdgcn_s_barrier()
; #define PG8_SCHED __builtin_amdgcn_sched_barrier(0)
; __device__ __forceinline__ void gemm_phase(LAS unsigned char* lds, const GemmD g, const Sched& S, const Epi& E) {
;     ...
;             PG8_LDB(B0, 1, 0); PG8_LDB(B1, 1, 1); PG8_SCHED; PG8_LDA(At, 1, 0); PG8_STAGE(PG8_SA(0, 1), a2 + hstepA, voffA);
;             PG8_WAIT_V(8); PG8_WAIT_L(0); PG8_BAR; PG8_MMA(0, 0, At, B0); PG8_MMA(0, 1, At, B1); PG8_BAR; PG8_SCHED;
;             PG8_LDA(At, 1, 1); PG8_STAGE(PG8_SB(1, 0), b3, voffB); PG8_STAGE(PG8_SB(1, 1), b3 + hstepB, voffB); PG8_STAGE(PG8_SA(1, 0), a3, voffA);
;             PG8_WAIT_V(8); PG8_WAIT_L(0); PG8_BAR; PG8_MMA(1, 0, At, B0); PG8_MMA(1, 1, At, B1); PG8_BAR; PG8_SCHED;
;         }
	s_add_i32 s22, 0, 0x18000
	s_add_i32 s23, 0, 0x1c000
	ds_read_b128 v[130:133], v242
	ds_read_b128 v[146:149], v242 offset:1024
	ds_read_b128 v[150:153], v242 offset:2048
	ds_read_b128 v[154:157], v242 offset:3072
	ds_read_b128 v[162:165], v243
	ds_read_b128 v[166:169], v243 offset:1024
	ds_read_b128 v[170:173], v243 offset:2048
	ds_read_b128 v[174:177], v243 offset:3072
	s_mov_b32 m0, s15
	ds_read_b128 v[182:185], v161 offset:32768
	ds_read_b128 v[186:189], v161 offset:33792
	ds_read_b128 v[190:193], v161 offset:34816
	ds_read_b128 v[216:219], v161 offset:35840
	ds_read_b128 v[220:223], v161 offset:36864
	ds_read_b128 v[224:227], v161 offset:37888
	ds_read_b128 v[228:231], v161 offset:38912
	ds_read_b128 v[236:239], v161 offset:39936
	global_load_lds_dwordx4 v142, s[26:27]
	s_mov_b32 m0, s10
	s_nop 0
	global_load_lds_dwordx4 v144, s[26:27]
	s_waitcnt vmcnt(8)
	s_waitcnt lgkmcnt(0)
	s_barrier
	s_waitcnt lgkmcnt(0)
	v_mfma_f32_16x16x32_bf16 v[126:129], v[130:133], v[182:185], v[126:129]
	v_mfma_f32_16x16x32_bf16 v[122:125], v[150:153], v[182:185], v[122:125]
	v_mfma_f32_16x16x32_bf16 v[110:113], v[130:133], v[190:193], v[110:113]
	v_mfma_f32_16x16x32_bf16 v[106:109], v[150:153], v[190:193], v[106:109]
	v_mfma_f32_16x16x32_bf16 v[94:97], v[130:133], v[220:223], v[94:97]
	v_mfma_f32_16x16x32_bf16 v[90:93], v[150:153], v[220:223], v[90:93]
	v_mfma_f32_16x16x32_bf16 v[78:81], v[130:133], v[228:231], v[78:81]
	v_mfma_f32_16x16x32_bf16 v[74:77], v[150:153], v[228:231], v[74:77]
	v_mfma_f32_16x16x32_bf16 v[126:129], v[146:149], v[186:189], v[126:129]
	v_mfma_f32_16x16x32_bf16 v[122:125], v[154:157], v[186:189], v[122:125]
	v_mfma_f32_16x16x32_bf16 v[110:113], v[146:149], v[216:219], v[110:113]
	v_mfma_f32_16x16x32_bf16 v[106:109], v[154:157], v[216:219], v[106:109]
	v_mfma_f32_16x16x32_bf16 v[94:97], v[146:149], v[224:227], v[94:97]
	v_mfma_f32_16x16x32_bf16 v[90:93], v[154:157], v[224:227], v[90:93]
	v_mfma_f32_16x16x32_bf16 v[78:81], v[146:149], v[236:239], v[78:81]
	v_mfma_f32_16x16x32_bf16 v[74:77], v[154:157], v[236:239], v[74:77]
	v_mfma_f32_16x16x32_bf16 v[118:121], v[162:165], v[182:185], v[118:121]
	v_mfma_f32_16x16x32_bf16 v[114:117], v[170:173], v[182:185], v[114:117]
	v_mfma_f32_16x16x32_bf16 v[102:105], v[162:165], v[190:193], v[102:105]
	v_mfma_f32_16x16x32_bf16 v[98:101], v[170:173], v[190:193], v[98:101]
	v_mfma_f32_16x16x32_bf16 v[86:89], v[162:165], v[220:223], v[86:89]
	v_mfma_f32_16x16x32_bf16 v[82:85], v[170:173], v[220:223], v[82:85]
	v_mfma_f32_16x16x32_bf16 v[70:73], v[162:165], v[228:231], v[70:73]
	v_mfma_f32_16x16x32_bf16 v[66:69], v[170:173], v[228:231], v[66:69]
	v_mfma_f32_16x16x32_bf16 v[118:121], v[166:169], v[186:189], v[118:121]
	v_mfma_f32_16x16x32_bf16 v[114:117], v[174:177], v[186:189], v[114:117]
	v_mfma_f32_16x16x32_bf16 v[102:105], v[166:169], v[216:219], v[102:105]
	v_mfma_f32_16x16x32_bf16 v[98:101], v[174:177], v[216:219], v[98:101]
	v_mfma_f32_16x16x32_bf16 v[86:89], v[166:169], v[224:227], v[86:89]
	v_mfma_f32_16x16x32_bf16 v[82:85], v[174:177], v[224:227], v[82:85]
	v_mfma_f32_16x16x32_bf16 v[70:73], v[166:169], v[236:239], v[70:73]
	v_mfma_f32_16x16x32_bf16 v[66:69], v[174:177], v[236:239], v[66:69]
	s_barrier
	s_add_i32 s22, s22, s30
	s_add_u32 vcc_lo, vcc_lo, s84
	s_addc_u32 vcc_hi, vcc_hi, s85
	s_add_u32 s26, s26, s84
	s_addc_u32 s27, s27, s85
	s_mov_b32 m0, s22
	ds_read_b128 v[182:185], v161 offset:49152
	ds_read_b128 v[186:189], v161 offset:50176
	ds_read_b128 v[190:193], v161 offset:51200
	ds_read_b128 v[216:219], v161 offset:52224
	ds_read_b128 v[220:223], v161 offset:53248
	ds_read_b128 v[224:227], v161 offset:54272
	ds_read_b128 v[228:231], v161 offset:55296
	ds_read_b128 v[236:239], v161 offset:56320
	global_load_lds_dwordx4 v136, vcc
	s_add_i32 m0, s22, 0x2000
	s_add_i32 s22, s23, s30
	global_load_lds_dwordx4 v140, vcc
	s_mov_b32 m0, s22
	s_nop 0
	global_load_lds_dwordx4 v253, vcc
	s_add_i32 m0, s22, 0x2000
	s_nop 0
	global_load_lds_dwordx4 v254, vcc
	s_mov_b32 m0, s18
	s_add_u32 s8, s8, 0x100
	global_load_lds_dwordx4 v134, s[26:27]
	s_mov_b32 m0, s19
	s_addc_u32 s9, s9, 0
	global_load_lds_dwordx4 v138, s[26:27]
	s_mov_b32 s26, s92
	s_cmp_ge_u32 s92, s12
	s_waitcnt vmcnt(8)
	s_waitcnt lgkmcnt(0)
	s_barrier
	s_waitcnt lgkmcnt(0)
	v_mfma_f32_16x16x32_bf16 v[62:65], v[130:133], v[182:185], v[62:65]
	v_mfma_f32_16x16x32_bf16 v[58:61], v[150:153], v[182:185], v[58:61]
	v_mfma_f32_16x16x32_bf16 v[46:49], v[130:133], v[190:193], v[46:49]
	v_mfma_f32_16x16x32_bf16 v[42:45], v[150:153], v[190:193], v[42:45]
	v_mfma_f32_16x16x32_bf16 v[30:33], v[130:133], v[220:223], v[30:33]
	v_mfma_f32_16x16x32_bf16 v[26:29], v[150:153], v[220:223], v[26:29]
	v_mfma_f32_16x16x32_bf16 v[14:17], v[130:133], v[228:231], v[14:17]
	v_mfma_f32_16x16x32_bf16 v[10:13], v[150:153], v[228:231], v[10:13]
	v_mfma_f32_16x16x32_bf16 v[62:65], v[146:149], v[186:189], v[62:65]
	v_mfma_f32_16x16x32_bf16 v[58:61], v[154:157], v[186:189], v[58:61]
	v_mfma_f32_16x16x32_bf16 v[46:49], v[146:149], v[216:219], v[46:49]
	v_mfma_f32_16x16x32_bf16 v[42:45], v[154:157], v[216:219], v[42:45]
	v_mfma_f32_16x16x32_bf16 v[30:33], v[146:149], v[224:227], v[30:33]
	v_mfma_f32_16x16x32_bf16 v[26:29], v[154:157], v[224:227], v[26:29]
	v_mfma_f32_16x16x32_bf16 v[14:17], v[146:149], v[236:239], v[14:17]
	v_mfma_f32_16x16x32_bf16 v[10:13], v[154:157], v[236:239], v[10:13]
	v_mfma_f32_16x16x32_bf16 v[54:57], v[162:165], v[182:185], v[54:57]
	v_mfma_f32_16x16x32_bf16 v[50:53], v[170:173], v[182:185], v[50:53]
	v_mfma_f32_16x16x32_bf16 v[38:41], v[162:165], v[190:193], v[38:41]
	v_mfma_f32_16x16x32_bf16 v[34:37], v[170:173], v[190:193], v[34:37]
	v_mfma_f32_16x16x32_bf16 v[22:25], v[162:165], v[220:223], v[22:25]
	v_mfma_f32_16x16x32_bf16 v[18:21], v[170:173], v[220:223], v[18:21]
	v_mfma_f32_16x16x32_bf16 v[6:9], v[162:165], v[228:231], v[6:9]
	v_mfma_f32_16x16x32_bf16 v[2:5], v[170:173], v[228:231], v[2:5]
	v_mfma_f32_16x16x32_bf16 v[54:57], v[166:169], v[186:189], v[54:57]
	v_mfma_f32_16x16x32_bf16 v[50:53], v[174:177], v[186:189], v[50:53]
	v_mfma_f32_16x16x32_bf16 v[38:41], v[166:169], v[216:219], v[38:41]
	v_mfma_f32_16x16x32_bf16 v[34:37], v[174:177], v[216:219], v[34:37]
	v_mfma_f32_16x16x32_bf16 v[22:25], v[166:169], v[224:227], v[22:25]
	v_mfma_f32_16x16x32_bf16 v[18:21], v[174:177], v[224:227], v[18:21]
	v_mfma_f32_16x16x32_bf16 v[6:9], v[166:169], v[236:239], v[6:9]
	v_mfma_f32_16x16x32_bf16 v[2:5], v[174:177], v[236:239], v[2:5]
	s_barrier
	s_cbranch_scc0 .LBB0_215
	s_branch .Lgemm_after
; #define PG8_STAGE(bufoff, gbase, voff) do { _Pragma("unroll") for (int _i = 0; _i < 2; ++_i) \
;         __builtin_amdgcn_global_load_lds((const unsigned*)((const char*)(gbase) + (voff)[_i]), (LAS unsigned*)(lds + (bufoff) + ldsw + _i * 8192), 16, 0, 0); } while (0)
; #define PG8_LDA(dst, b, h) do { _Pragma("unroll") for (int m = 0; m < 4; ++m) _Pragma("unroll") for (int k = 0; k < 2; ++k) dst[m][k] = *(const LAS bf16x8*)(lds + PG8_SA(b, h) + aoff + m * 2048 + k * 1024); } while (0)
; #define PG8_LDB(dst, b, h) do { _Pragma("unroll") for (int n = 0; n < 2; ++n) _Pragma("unroll") for (int k = 0; k < 2; ++k) dst[n][k] = *(const LAS bf16x8*)(lds + PG8_SB(b, h) + boff + n * 2048 + k * 1024); } while (0)
; #define PG8_MMA(ai, bj, At, Bt) do { __builtin_amdgcn_s_setprio(1); _Pragma("unroll") for (int m = 0; m < 4; ++m) _Pragma("unroll") for (int n = 0; n < 2; ++n) _Pragma("unroll") for (int k = 0; k < 2; ++k) \
;         acc[ai][bj][m][n] = __builtin_amdgcn_mfma_f32_16x16x32_bf16(Bt[n][k], At[m][k], acc[ai][bj][m][n], 0, 0, 0); __builtin_amdgcn_s_setprio(0); } while (0)
; #define PG8_WAIT_V(n) asm volatile("s_waitcnt vmcnt(" #n ")" ::: "memory")
; #define PG8_WAIT_L(n) asm volatile("s_waitcnt lgkmcnt(" #n ")" ::: "memory")
; #define PG8_BAR __builtin_amdgcn_s_barrier()
; #define PG8_SCHED __builtin_amdgcn_sched_barrier(0)
; __device__ __forceinline__ void gemm_phase(LAS unsigned char* lds, const GemmD g, const Sched& S, const Epi& E) {
;     ...
;         for (int t = 0; t < nt; t += 2) {
;             const bool last = (t == nt - 2);
;             const char* a1 = cA + (size_t)(t + 1) * kstep;
;             const char* a2 = last ? nA : cA + (size_t)(t + 2) * kstep; const char* b2 = last ? nB : cB + (size_t)(t + 2) * kstep;
;             const char* a3 = a2 + kstep; const char* b3 = b2 + kstep;
;             PG8_LDB(B0, 0, 0); PG8_LDB(B1, 0, 1); PG8_SCHED; PG8_LDA(At, 0, 0); PG8_STAGE(PG8_SA(1, 1), a1 + hstepA, voffA);
;             PG8_WAIT_V(8); PG8_WAIT_L(0); PG8_BAR; PG8_MMA(0, 0, At, B0); PG8_MMA(0, 1, At, B1); PG8_BAR; PG8_SCHED;
;             PG8_LDA(At, 0, 1); PG8_STAGE(PG8_SB(0, 0), b2, voffB); PG8_STAGE(PG8_SB(0, 1), b2 + hstepB, voffB); PG8_STAGE(PG8_SA(0, 0), a2, voffA);
;             PG8_WAIT_V(8); PG8_WAIT_L(0); PG8_BAR; PG8_MMA(1, 0, At, B0); PG8_MMA(1, 1, At, B1); PG8_BAR; PG8_SCHED;
.LBB0_215:
	ds_read_b128 v[130:133], v240
	ds_read_b128 v[146:149], v240 offset:1024
	ds_read_b128 v[150:153], v240 offset:2048
	ds_read_b128 v[154:157], v240 offset:3072
	ds_read_b128 v[162:165], v241
	ds_read_b128 v[166:169], v241 offset:1024
	ds_read_b128 v[170:173], v241 offset:2048
	ds_read_b128 v[174:177], v241 offset:3072
	s_add_i32 m0, s31, 0xc000
	ds_read_b128 v[182:185], v161
	ds_read_b128 v[186:189], v161 offset:1024
	ds_read_b128 v[190:193], v161 offset:2048
	ds_read_b128 v[216:219], v161 offset:3072
	ds_read_b128 v[220:223], v161 offset:4096
	ds_read_b128 v[224:227], v161 offset:5120
	ds_read_b128 v[228:231], v161 offset:6144
	ds_read_b128 v[236:239], v161 offset:7168
	global_load_lds_dwordx4 v142, s[8:9]
	s_add_i32 m0, s31, 0xe000
	s_nop 0
	global_load_lds_dwordx4 v144, s[8:9]
	s_add_i32 s92, s26, 2
	s_add_u32 s93, s8, 0x80
	s_addc_u32 s27, s9, 0
	s_add_i32 s22, 0, 0x10000
	s_cmp_eq_u32 s11, s26
	s_cselect_b32 s27, s1, s27
	s_cselect_b32 s26, s0, s93
	s_cselect_b32 vcc_hi, s17, s35
	s_cselect_b32 vcc_lo, s16, s34
	s_add_i32 s23, 0, 0x14000
	s_waitcnt vmcnt(8)
	s_waitcnt lgkmcnt(0)
	s_barrier
	s_waitcnt lgkmcnt(0)
	v_mfma_f32_16x16x32_bf16 v[126:129], v[130:133], v[182:185], v[126:129]
	v_mfma_f32_16x16x32_bf16 v[122:125], v[150:153], v[182:185], v[122:125]
	v_mfma_f32_16x16x32_bf16 v[110:113], v[130:133], v[190:193], v[110:113]
	v_mfma_f32_16x16x32_bf16 v[106:109], v[150:153], v[190:193], v[106:109]
	v_mfma_f32_16x16x32_bf16 v[94:97], v[130:133], v[220:223], v[94:97]
	v_mfma_f32_16x16x32_bf16 v[90:93], v[150:153], v[220:223], v[90:93]
	v_mfma_f32_16x16x32_bf16 v[78:81], v[130:133], v[228:231], v[78:81]
	v_mfma_f32_16x16x32_bf16 v[74:77], v[150:153], v[228:231], v[74:77]
	v_mfma_f32_16x16x32_bf16 v[126:129], v[146:149], v[186:189], v[126:129]
	v_mfma_f32_16x16x32_bf16 v[122:125], v[154:157], v[186:189], v[122:125]
	v_mfma_f32_16x16x32_bf16 v[110:113], v[146:149], v[216:219], v[110:113]
	v_mfma_f32_16x16x32_bf16 v[106:109], v[154:157], v[216:219], v[106:109]
	v_mfma_f32_16x16x32_bf16 v[94:97], v[146:149], v[224:227], v[94:97]
	v_mfma_f32_16x16x32_bf16 v[90:93], v[154:157], v[224:227], v[90:93]
	v_mfma_f32_16x16x32_bf16 v[78:81], v[146:149], v[236:239], v[78:81]
	v_mfma_f32_16x16x32_bf16 v[74:77], v[154:157], v[236:239], v[74:77]
	v_mfma_f32_16x16x32_bf16 v[118:121], v[162:165], v[182:185], v[118:121]
	v_mfma_f32_16x16x32_bf16 v[114:117], v[170:173], v[182:185], v[114:117]
	v_mfma_f32_16x16x32_bf16 v[102:105], v[162:165], v[190:193], v[102:105]
	v_mfma_f32_16x16x32_bf16 v[98:101], v[170:173], v[190:193], v[98:101]
	v_mfma_f32_16x16x32_bf16 v[86:89], v[162:165], v[220:223], v[86:89]
	v_mfma_f32_16x16x32_bf16 v[82:85], v[170:173], v[220:223], v[82:85]
	v_mfma_f32_16x16x32_bf16 v[70:73], v[162:165], v[228:231], v[70:73]
	v_mfma_f32_16x16x32_bf16 v[66:69], v[170:173], v[228:231], v[66:69]
	v_mfma_f32_16x16x32_bf16 v[118:121], v[166:169], v[186:189], v[118:121]
	v_mfma_f32_16x16x32_bf16 v[114:117], v[174:177], v[186:189], v[114:117]
	v_mfma_f32_16x16x32_bf16 v[102:105], v[166:169], v[216:219], v[102:105]
	v_mfma_f32_16x16x32_bf16 v[98:101], v[174:177], v[216:219], v[98:101]
	v_mfma_f32_16x16x32_bf16 v[86:89], v[166:169], v[224:227], v[86:89]
	v_mfma_f32_16x16x32_bf16 v[82:85], v[174:177], v[224:227], v[82:85]
	v_mfma_f32_16x16x32_bf16 v[70:73], v[166:169], v[236:239], v[70:73]
	v_mfma_f32_16x16x32_bf16 v[66:69], v[174:177], v[236:239], v[66:69]
	s_barrier
	s_add_i32 s22, s22, s30
	s_mov_b32 m0, s22
	ds_read_b128 v[182:185], v161 offset:16384
	ds_read_b128 v[186:189], v161 offset:17408
	ds_read_b128 v[190:193], v161 offset:18432
	ds_read_b128 v[216:219], v161 offset:19456
	ds_read_b128 v[220:223], v161 offset:20480
	ds_read_b128 v[224:227], v161 offset:21504
	ds_read_b128 v[228:231], v161 offset:22528
	ds_read_b128 v[236:239], v161 offset:23552
	global_load_lds_dwordx4 v136, vcc
	s_add_i32 m0, s22, 0x2000
	s_add_i32 s22, s23, s30
	global_load_lds_dwordx4 v140, vcc
	s_mov_b32 m0, s22
	s_nop 0
	global_load_lds_dwordx4 v253, vcc
	s_add_i32 m0, s22, 0x2000
	s_nop 0
	global_load_lds_dwordx4 v254, vcc
	s_mov_b32 m0, s31
	s_add_u32 s34, s34, 0x100
	global_load_lds_dwordx4 v134, s[26:27]
	s_mov_b32 m0, s14
	s_addc_u32 s35, s35, 0
	global_load_lds_dwordx4 v138, s[26:27]
	s_waitcnt vmcnt(8)
	s_waitcnt lgkmcnt(0)
	s_barrier
	s_waitcnt lgkmcnt(0)
	v_mfma_f32_16x16x32_bf16 v[62:65], v[130:133], v[182:185], v[62:65]
	v_mfma_f32_16x16x32_bf16 v[58:61], v[150:153], v[182:185], v[58:61]
	v_mfma_f32_16x16x32_bf16 v[46:49], v[130:133], v[190:193], v[46:49]
	v_mfma_f32_16x16x32_bf16 v[42:45], v[150:153], v[190:193], v[42:45]
	v_mfma_f32_16x16x32_bf16 v[30:33], v[130:133], v[220:223], v[30:33]
	v_mfma_f32_16x16x32_bf16 v[26:29], v[150:153], v[220:223], v[26:29]
	v_mfma_f32_16x16x32_bf16 v[14:17], v[130:133], v[228:231], v[14:17]
	v_mfma_f32_16x16x32_bf16 v[10:13], v[150:153], v[228:231], v[10:13]
	v_mfma_f32_16x16x32_bf16 v[62:65], v[146:149], v[186:189], v[62:65]
	v_mfma_f32_16x16x32_bf16 v[58:61], v[154:157], v[186:189], v[58:61]
	v_mfma_f32_16x16x32_bf16 v[46:49], v[146:149], v[216:219], v[46:49]
	v_mfma_f32_16x16x32_bf16 v[42:45], v[154:157], v[216:219], v[42:45]
	v_mfma_f32_16x16x32_bf16 v[30:33], v[146:149], v[224:227], v[30:33]
	v_mfma_f32_16x16x32_bf16 v[26:29], v[154:157], v[224:227], v[26:29]
	v_mfma_f32_16x16x32_bf16 v[14:17], v[146:149], v[236:239], v[14:17]
	v_mfma_f32_16x16x32_bf16 v[10:13], v[154:157], v[236:239], v[10:13]
	v_mfma_f32_16x16x32_bf16 v[54:57], v[162:165], v[182:185], v[54:57]
	v_mfma_f32_16x16x32_bf16 v[50:53], v[170:173], v[182:185], v[50:53]
	v_mfma_f32_16x16x32_bf16 v[38:41], v[162:165], v[190:193], v[38:41]
	v_mfma_f32_16x16x32_bf16 v[34:37], v[170:173], v[190:193], v[34:37]
	v_mfma_f32_16x16x32_bf16 v[22:25], v[162:165], v[220:223], v[22:25]
	v_mfma_f32_16x16x32_bf16 v[18:21], v[170:173], v[220:223], v[18:21]
	v_mfma_f32_16x16x32_bf16 v[6:9], v[162:165], v[228:231], v[6:9]
	v_mfma_f32_16x16x32_bf16 v[2:5], v[170:173], v[228:231], v[2:5]
	v_mfma_f32_16x16x32_bf16 v[54:57], v[166:169], v[186:189], v[54:57]
	v_mfma_f32_16x16x32_bf16 v[50:53], v[174:177], v[186:189], v[50:53]
	v_mfma_f32_16x16x32_bf16 v[38:41], v[166:169], v[216:219], v[38:41]
	v_mfma_f32_16x16x32_bf16 v[34:37], v[174:177], v[216:219], v[34:37]
	v_mfma_f32_16x16x32_bf16 v[22:25], v[166:169], v[224:227], v[22:25]
	v_mfma_f32_16x16x32_bf16 v[18:21], v[174:177], v[224:227], v[18:21]
	v_mfma_f32_16x16x32_bf16 v[6:9], v[166:169], v[236:239], v[6:9]
	v_mfma_f32_16x16x32_bf16 v[2:5], v[174:177], v[236:239], v[2:5]
	s_barrier
; #define PG8_STAGE(bufoff, gbase, voff) do { _Pragma("unroll") for (int _i = 0; _i < 2; ++_i) \
;         __builtin_amdgcn_global_load_lds((const unsigned*)((const char*)(gbase) + (voff)[_i]), (LAS unsigned*)(lds + (bufoff) + ldsw + _i * 8192), 16, 0, 0); } while (0)
; #define PG8_LDA(dst, b, h) do { _Pragma("unroll") for (int m = 0; m < 4; ++m) _Pragma("unroll") for (int k = 0; k < 2; ++k) dst[m][k] = *(const LAS bf16x8*)(lds + PG8_SA(b, h) + aoff + m * 2048 + k * 1024); } while (0)
; #define PG8_LDB(dst, b, h) do { _Pragma("unroll") for (int n = 0; n < 2; ++n) _Pragma("unroll") for (int k = 0; k < 2; ++k) dst[n][k] = *(const LAS bf16x8*)(lds + PG8_SB(b, h) + boff + n * 2048 + k * 1024); } while (0)
; #define PG8_MMA(ai, bj, At, Bt) do { __builtin_amdgcn_s_setprio(1); _Pragma("unroll") for (int m = 0; m < 4; ++m) _Pragma("unroll") for (int n = 0; n < 2; ++n) _Pragma("unroll") for (int k = 0; k < 2; ++k) \
;         acc[ai][bj][m][n] = __builtin_amdgcn_mfma_f32_16x16x32_bf16(Bt[n][k], At[m][k], acc[ai][bj][m][n], 0, 0, 0); __builtin_amdgcn_s_setprio(0); } while (0)
; #define PG8_WAIT_V(n) asm volatile("s_waitcnt vmcnt(" #n ")" ::: "memory")
; #define PG8_WAIT_L(n) asm volatile("s_waitcnt lgkmcnt(" #n ")" ::: "memory")
; #define PG8_BAR __builtin_amdgcn_s_barrier()
; #define PG8_SCHED __builtin_amdgcn_sched_barrier(0)
; __device__ __forceinline__ void gemm_phase(LAS unsigned char* lds, const GemmD g, const Sched& S, const Epi& E) {
;     ...
;             PG8_LDB(B0, 1, 0); PG8_LDB(B1, 1, 1); PG8_SCHED; PG8_LDA(At, 1, 0); PG8_STAGE(PG8_SA(0, 1), a2 + hstepA, voffA);
;             PG8_WAIT_V(8); PG8_WAIT_L(0); PG8_BAR; PG8_MMA(0, 0, At, B0); PG8_MMA(0, 1, At, B1); PG8_BAR; PG8_SCHED;
;             PG8_LDA(At, 1, 1); PG8_STAGE(PG8_SB(1, 0), b3, voffB); PG8_STAGE(PG8_SB(1, 1), b3 + hstepB, voffB); PG8_STAGE(PG8_SA(1, 0), a3, voffA);
;             PG8_WAIT_V(8); PG8_WAIT_L(0); PG8_BAR; PG8_MMA(1, 0, At, B0); PG8_MMA(1, 1, At, B1); PG8_BAR; PG8_SCHED;
;         }
	s_add_i32 s22, 0, 0x18000
	s_add_i32 s23, 0, 0x1c000
	ds_read_b128 v[130:133], v242
	ds_read_b128 v[146:149], v242 offset:1024
	ds_read_b128 v[150:153], v242 offset:2048
	ds_read_b128 v[154:157], v242 offset:3072
	ds_read_b128 v[162:165], v243
	ds_read_b128 v[166:169], v243 offset:1024
	ds_read_b128 v[170:173], v243 offset:2048
	ds_read_b128 v[174:177], v243 offset:3072
	s_mov_b32 m0, s15
	ds_read_b128 v[182:185], v161 offset:32768
	ds_read_b128 v[186:189], v161 offset:33792
	ds_read_b128 v[190:193], v161 offset:34816
	ds_read_b128 v[216:219], v161 offset:35840
	ds_read_b128 v[220:223], v161 offset:36864
	ds_read_b128 v[224:227], v161 offset:37888
	ds_read_b128 v[228:231], v161 offset:38912
	ds_read_b128 v[236:239], v161 offset:39936
	global_load_lds_dwordx4 v142, s[26:27]
	s_mov_b32 m0, s10
	s_nop 0
	global_load_lds_dwordx4 v144, s[26:27]
	s_waitcnt vmcnt(8)
	s_waitcnt lgkmcnt(0)
	s_barrier
	s_waitcnt lgkmcnt(0)
	v_mfma_f32_16x16x32_bf16 v[126:129], v[130:133], v[182:185], v[126:129]
	v_mfma_f32_16x16x32_bf16 v[122:125], v[150:153], v[182:185], v[122:125]
	v_mfma_f32_16x16x32_bf16 v[110:113], v[130:133], v[190:193], v[110:113]
	v_mfma_f32_16x16x32_bf16 v[106:109], v[150:153], v[190:193], v[106:109]
	v_mfma_f32_16x16x32_bf16 v[94:97], v[130:133], v[220:223], v[94:97]
	v_mfma_f32_16x16x32_bf16 v[90:93], v[150:153], v[220:223], v[90:93]
	v_mfma_f32_16x16x32_bf16 v[78:81], v[130:133], v[228:231], v[78:81]
	v_mfma_f32_16x16x32_bf16 v[74:77], v[150:153], v[228:231], v[74:77]
	v_mfma_f32_16x16x32_bf16 v[126:129], v[146:149], v[186:189], v[126:129]
	v_mfma_f32_16x16x32_bf16 v[122:125], v[154:157], v[186:189], v[122:125]
	v_mfma_f32_16x16x32_bf16 v[110:113], v[146:149], v[216:219], v[110:113]
	v_mfma_f32_16x16x32_bf16 v[106:109], v[154:157], v[216:219], v[106:109]
	v_mfma_f32_16x16x32_bf16 v[94:97], v[146:149], v[224:227], v[94:97]
	v_mfma_f32_16x16x32_bf16 v[90:93], v[154:157], v[224:227], v[90:93]
	v_mfma_f32_16x16x32_bf16 v[78:81], v[146:149], v[236:239], v[78:81]
	v_mfma_f32_16x16x32_bf16 v[74:77], v[154:157], v[236:239], v[74:77]
	v_mfma_f32_16x16x32_bf16 v[118:121], v[162:165], v[182:185], v[118:121]
	v_mfma_f32_16x16x32_bf16 v[114:117], v[170:173], v[182:185], v[114:117]
	v_mfma_f32_16x16x32_bf16 v[102:105], v[162:165], v[190:193], v[102:105]
	v_mfma_f32_16x16x32_bf16 v[98:101], v[170:173], v[190:193], v[98:101]
	v_mfma_f32_16x16x32_bf16 v[86:89], v[162:165], v[220:223], v[86:89]
	v_mfma_f32_16x16x32_bf16 v[82:85], v[170:173], v[220:223], v[82:85]
	v_mfma_f32_16x16x32_bf16 v[70:73], v[162:165], v[228:231], v[70:73]
	v_mfma_f32_16x16x32_bf16 v[66:69], v[170:173], v[228:231], v[66:69]
	v_mfma_f32_16x16x32_bf16 v[118:121], v[166:169], v[186:189], v[118:121]
	v_mfma_f32_16x16x32_bf16 v[114:117], v[174:177], v[186:189], v[114:117]
	v_mfma_f32_16x16x32_bf16 v[102:105], v[166:169], v[216:219], v[102:105]
	v_mfma_f32_16x16x32_bf16 v[98:101], v[174:177], v[216:219], v[98:101]
	v_mfma_f32_16x16x32_bf16 v[86:89], v[166:169], v[224:227], v[86:89]
	v_mfma_f32_16x16x32_bf16 v[82:85], v[174:177], v[224:227], v[82:85]
	v_mfma_f32_16x16x32_bf16 v[70:73], v[166:169], v[236:239], v[70:73]
	v_mfma_f32_16x16x32_bf16 v[66:69], v[174:177], v[236:239], v[66:69]
	s_barrier
	s_add_i32 s22, s22, s30
	s_add_u32 vcc_lo, vcc_lo, s84
	s_addc_u32 vcc_hi, vcc_hi, s85
	s_add_u32 s26, s26, s84
	s_addc_u32 s27, s27, s85
	s_mov_b32 m0, s22
	ds_read_b128 v[182:185], v161 offset:49152
	ds_read_b128 v[186:189], v161 offset:50176
	ds_read_b128 v[190:193], v161 offset:51200
	ds_read_b128 v[216:219], v161 offset:52224
	ds_read_b128 v[220:223], v161 offset:53248
	ds_read_b128 v[224:227], v161 offset:54272
	ds_read_b128 v[228:231], v161 offset:55296
	ds_read_b128 v[236:239], v161 offset:56320
	global_load_lds_dwordx4 v136, vcc
	s_add_i32 m0, s22, 0x2000
	s_add_i32 s22, s23, s30
	global_load_lds_dwordx4 v140, vcc
	s_mov_b32 m0, s22
	s_nop 0
	global_load_lds_dwordx4 v253, vcc
	s_add_i32 m0, s22, 0x2000
	s_nop 0
	global_load_lds_dwordx4 v254, vcc
	s_mov_b32 m0, s18
	s_add_u32 s8, s8, 0x100
	global_load_lds_dwordx4 v134, s[26:27]
	s_mov_b32 m0, s19
	s_addc_u32 s9, s9, 0
	global_load_lds_dwordx4 v138, s[26:27]
	s_mov_b32 s26, s92
	s_cmp_ge_u32 s92, s12
	s_waitcnt vmcnt(8)
	s_waitcnt lgkmcnt(0)
	s_barrier
	s_waitcnt lgkmcnt(0)
	v_mfma_f32_16x16x32_bf16 v[62:65], v[130:133], v[182:185], v[62:65]
	v_mfma_f32_16x16x32_bf16 v[58:61], v[150:153], v[182:185], v[58:61]
	v_mfma_f32_16x16x32_bf16 v[46:49], v[130:133], v[190:193], v[46:49]
	v_mfma_f32_16x16x32_bf16 v[42:45], v[150:153], v[190:193], v[42:45]
	v_mfma_f32_16x16x32_bf16 v[30:33], v[130:133], v[220:223], v[30:33]
	v_mfma_f32_16x16x32_bf16 v[26:29], v[150:153], v[220:223], v[26:29]
	v_mfma_f32_16x16x32_bf16 v[14:17], v[130:133], v[228:231], v[14:17]
	v_mfma_f32_16x16x32_bf16 v[10:13], v[150:153], v[228:231], v[10:13]
	v_mfma_f32_16x16x32_bf16 v[62:65], v[146:149], v[186:189], v[62:65]
	v_mfma_f32_16x16x32_bf16 v[58:61], v[154:157], v[186:189], v[58:61]
	v_mfma_f32_16x16x32_bf16 v[46:49], v[146:149], v[216:219], v[46:49]
	v_mfma_f32_16x16x32_bf16 v[42:45], v[154:157], v[216:219], v[42:45]
	v_mfma_f32_16x16x32_bf16 v[30:33], v[146:149], v[224:227], v[30:33]
	v_mfma_f32_16x16x32_bf16 v[26:29], v[154:157], v[224:227], v[26:29]
	v_mfma_f32_16x16x32_bf16 v[14:17], v[146:149], v[236:239], v[14:17]
	v_mfma_f32_16x16x32_bf16 v[10:13], v[154:157], v[236:239], v[10:13]
	v_mfma_f32_16x16x32_bf16 v[54:57], v[162:165], v[182:185], v[54:57]
	v_mfma_f32_16x16x32_bf16 v[50:53], v[170:173], v[182:185], v[50:53]
	v_mfma_f32_16x16x32_bf16 v[38:41], v[162:165], v[190:193], v[38:41]
	v_mfma_f32_16x16x32_bf16 v[34:37], v[170:173], v[190:193], v[34:37]
	v_mfma_f32_16x16x32_bf16 v[22:25], v[162:165], v[220:223], v[22:25]
	v_mfma_f32_16x16x32_bf16 v[18:21], v[170:173], v[220:223], v[18:21]
	v_mfma_f32_16x16x32_bf16 v[6:9], v[162:165], v[228:231], v[6:9]
	v_mfma_f32_16x16x32_bf16 v[2:5], v[170:173], v[228:231], v[2:5]
	v_mfma_f32_16x16x32_bf16 v[54:57], v[166:169], v[186:189], v[54:57]
	v_mfma_f32_16x16x32_bf16 v[50:53], v[174:177], v[186:189], v[50:53]
	v_mfma_f32_16x16x32_bf16 v[38:41], v[166:169], v[216:219], v[38:41]
	v_mfma_f32_16x16x32_bf16 v[34:37], v[174:177], v[216:219], v[34:37]
	v_mfma_f32_16x16x32_bf16 v[22:25], v[166:169], v[224:227], v[22:25]
	v_mfma_f32_16x16x32_bf16 v[18:21], v[174:177], v[224:227], v[18:21]
	v_mfma_f32_16x16x32_bf16 v[6:9], v[166:169], v[236:239], v[6:9]
	v_mfma_f32_16x16x32_bf16 v[2:5], v[174:177], v[236:239], v[2:5]
	s_barrier
	s_cbranch_scc0 .LBB0_215
